# grid barrier release: every workgroup polls the monotonic cross-XCD arrival counter (no generation words, no leader round trips); XCD leader still does the single L2 writeback
# speedup vs baseline: 1.0403x; 1.0027x over previous
.LBB0_20:
	v_readlane_b32 s2, v251, 0
	v_readlane_b32 s3, v251, 1
	s_add_u32 s2, s2, 0xc8
	s_addc_u32 s3, s3, 0
	s_add_u32 s64, s60, 0x5480200
	s_addc_u32 s65, s61, 0
	s_add_u32 s66, s60, 0x5480400
	s_addc_u32 s67, s61, 0
	s_add_u32 s68, s60, 0x5480500
	s_addc_u32 s69, s61, 0
	s_add_u32 s70, s60, 0x5480600
	s_addc_u32 s71, s61, 0
	s_add_u32 s72, s60, 0x5480700
	s_addc_u32 s73, s61, 0
	s_add_u32 s74, s60, 0x5480800
	s_addc_u32 s75, s61, 0
	s_add_u32 s78, s60, 0x5480900
	s_addc_u32 s79, s61, 0
	s_add_u32 s76, s60, 0x5480a00
	s_addc_u32 s77, s61, 0
	s_add_u32 s20, s60, 0x5480b00
	s_addc_u32 s21, s61, 0
	s_add_u32 s22, s60, 0x5480c00
	s_addc_u32 s23, s61, 0
	s_add_u32 s24, s60, 0x5480d00
	s_addc_u32 s25, s61, 0
	s_add_u32 s26, s60, 0x5480e00
	s_addc_u32 s27, s61, 0
	s_add_u32 s28, s60, 0x5480f00
	s_addc_u32 s29, s61, 0
	s_add_u32 s30, s60, 0x5481000
	v_writelane_b32 v251, s2, 2
	s_addc_u32 s31, s61, 0
	s_mov_b32 s36, 0
	v_writelane_b32 v251, s3, 3
	s_add_u32 s2, s60, 0x5481100
	s_addc_u32 s3, s61, 0
	v_writelane_b32 v251, s2, 4
	v_mov_b32_e32 v32, 0
	v_mbcnt_lo_u32_b32 v0, -1, 0
	v_writelane_b32 v251, s3, 5
	s_add_u32 s2, s60, 0x5481200
	s_addc_u32 s3, s61, 0
	v_writelane_b32 v251, s2, 6
	s_mov_b32 s37, 1
	v_mov_b32_e32 v187, -1
	v_writelane_b32 v251, s3, 7
	s_add_u32 s2, s60, 0x5481300
	s_addc_u32 s3, s61, 0
	v_writelane_b32 v251, s2, 8
	s_cmp_eq_u32 s6, 15
	v_mov_b32_e32 v188, 1
	v_writelane_b32 v251, s3, 9
	s_cselect_b64 s[2:3], -1, 0
	v_writelane_b32 v251, s2, 10
	s_cmp_eq_u32 s6, 14
	v_mov_b32_e32 v189, 0x358637bd
	v_writelane_b32 v251, s3, 11
	s_cselect_b64 s[2:3], -1, 0
	v_writelane_b32 v251, s2, 12
	s_cmp_eq_u32 s6, 13
	v_mov_b32_e32 v190, 0x260
	v_writelane_b32 v251, s3, 13
	s_cselect_b64 s[2:3], -1, 0
	v_writelane_b32 v251, s2, 14
	s_cmp_eq_u32 s6, 12
	v_mbcnt_hi_u32_b32 v191, -1, v0
	v_writelane_b32 v251, s3, 15
	s_cselect_b64 s[2:3], -1, 0
	v_writelane_b32 v251, s2, 16
	s_cmp_eq_u32 s6, 11
	v_mov_b32_e32 v66, 0
	v_writelane_b32 v251, s3, 17
	s_cselect_b64 s[2:3], -1, 0
	v_writelane_b32 v251, s2, 18
	s_cmp_eq_u32 s6, 10
	v_mov_b32_e32 v67, v32
	v_writelane_b32 v251, s3, 19
	s_cselect_b64 s[2:3], -1, 0
	v_writelane_b32 v251, s2, 20
	s_cmp_eq_u32 s6, 9
	v_mov_b32_e32 v68, v32
	v_writelane_b32 v251, s3, 21
	s_cselect_b64 s[2:3], -1, 0
	v_writelane_b32 v251, s2, 22
	s_cmp_eq_u32 s6, 8
	v_mov_b32_e32 v69, v32
	v_writelane_b32 v251, s3, 23
	s_cselect_b64 s[2:3], -1, 0
	v_writelane_b32 v251, s2, 24
	s_cmp_eq_u32 s6, 7
	v_mov_b32_e32 v192, 0x2cb0
	v_writelane_b32 v251, s3, 25
	s_cselect_b64 s[2:3], -1, 0
	v_writelane_b32 v251, s2, 26
	s_cmp_eq_u32 s6, 6
	v_mov_b32_e32 v193, 0xb2c00
	v_writelane_b32 v251, s3, 27
	s_cselect_b64 s[2:3], -1, 0
	v_writelane_b32 v251, s2, 28
	s_cmp_eq_u32 s6, 5
	v_mov_b32_e32 v194, 0x86f
	v_writelane_b32 v251, s3, 29
	s_cselect_b64 s[2:3], -1, 0
	v_writelane_b32 v251, s2, 30
	s_cmp_eq_u32 s6, 4
	v_mov_b64_e32 v[150:151], 0x100
	v_writelane_b32 v251, s3, 31
	s_cselect_b64 s[2:3], -1, 0
	v_writelane_b32 v251, s2, 32
	s_cmp_eq_u32 s6, 3
	v_mov_b64_e32 v[152:153], 0xff
	v_writelane_b32 v251, s3, 33
	s_cselect_b64 s[2:3], -1, 0
	v_writelane_b32 v251, s2, 34
	s_cmp_eq_u32 s6, 2
	v_mov_b32_e32 v195, 0x41b17218
	v_writelane_b32 v251, s3, 35
	s_cselect_b64 s[2:3], -1, 0
	v_writelane_b32 v251, s2, 36
	s_cmp_eq_u32 s6, 1
	s_movk_i32 s83, 0x2cb0
	v_writelane_b32 v251, s3, 37
	s_cselect_b64 s[2:3], -1, 0
	v_writelane_b32 v251, s2, 38
	s_cmp_eq_u32 s6, 0
	s_mov_b32 s33, 0xff800000
	v_writelane_b32 v251, s3, 39
	s_cselect_b64 s[2:3], -1, 0
	v_writelane_b32 v251, s2, 40
	s_movk_i32 s35, 0x100
	s_movk_i32 s34, 0xbf
	v_writelane_b32 v251, s3, 41
	s_lshl_b32 s2, s6, 8
	s_add_u32 s0, s0, s2
	s_addc_u32 s1, s1, 0
	s_add_u32 s2, s0, 0x1400
	s_addc_u32 s3, s1, 0
	v_writelane_b32 v251, s2, 42
	s_add_u32 s0, s0, 0x2400
	s_addc_u32 s1, s1, 0
	v_writelane_b32 v251, s3, 43
	v_writelane_b32 v251, s0, 44
	s_brev_b32 s97, 1
	s_movk_i32 s94, 0x670
	v_writelane_b32 v251, s1, 45
	s_add_u32 s0, s60, 0x5483400
	s_addc_u32 s1, s61, 0
	v_writelane_b32 v251, s0, 46
	s_mov_b32 s92, 0x20000
	s_mov_b32 s93, 0x80000
	v_writelane_b32 v251, s1, 47
	s_add_u32 s0, s60, 0x5483500
	s_addc_u32 s1, s61, 0
	v_writelane_b32 v251, s0, 48
	s_add_i32 s96, 0, 0x20800
	s_add_i32 s95, 0, 0x22800
	v_writelane_b32 v251, s1, 49
	s_add_i32 s0, 0, 0x2800
	v_writelane_b32 v251, s0, 50
	s_add_i32 s0, 0, 0x2c00
	v_writelane_b32 v251, s0, 51
	s_add_i32 s0, 0, 0x3000
	v_writelane_b32 v251, s0, 52
	s_add_i32 s0, 0, 0x3400
	v_writelane_b32 v251, s0, 53
	s_add_i32 s0, 0, 0x14d00
	v_writelane_b32 v251, s0, 54
	s_add_i32 s0, 0, 0x20400
	v_writelane_b32 v251, s0, 55
	s_add_i32 s0, 0, 0x20404
	v_writelane_b32 v251, s0, 56
	v_cmp_eq_u32_e64 s[0:1], 0, v186
	s_mov_b32 s88, 0x90000
	s_mov_b32 s89, 0xa0000
	v_writelane_b32 v251, s0, 57
	s_mov_b32 s85, 0xb0000
	s_movk_i32 s86, 0x7fff
	v_writelane_b32 v251, s1, 58
	v_writelane_b32 v251, s64, 59
	s_movk_i32 s87, 0x1600
	s_mov_b64 s[80:81], 0x165800
	v_writelane_b32 v251, s65, 60
	v_writelane_b32 v251, s66, 61
	s_mov_b64 s[60:61], 0x80
	s_nop 0
	v_writelane_b32 v251, s67, 62
	v_writelane_b32 v251, s68, 63
	s_nop 1
	v_writelane_b32 v252, s69, 0
	v_writelane_b32 v252, s70, 1
	s_nop 1
	v_writelane_b32 v252, s71, 2
	v_writelane_b32 v252, s72, 3
	s_nop 1
	v_writelane_b32 v252, s73, 4
	v_writelane_b32 v252, s74, 5
	s_nop 1
	v_writelane_b32 v252, s75, 6
	v_writelane_b32 v252, s78, 7
	s_nop 1
	v_writelane_b32 v252, s79, 8
	v_writelane_b32 v252, s76, 9
	s_nop 1
	v_writelane_b32 v252, s77, 10
	v_writelane_b32 v252, s40, 11
	v_writelane_b32 v252, s20, 12
	s_nop 1
	v_writelane_b32 v252, s21, 13
	v_writelane_b32 v252, s22, 14
	s_nop 1
	v_writelane_b32 v252, s23, 15
	v_writelane_b32 v252, s24, 16
	s_nop 1
	v_writelane_b32 v252, s25, 17
	v_writelane_b32 v252, s26, 18
	s_nop 1
	v_writelane_b32 v252, s27, 19
	v_writelane_b32 v252, s28, 20
	s_nop 1
	v_writelane_b32 v252, s29, 21
	v_writelane_b32 v252, s30, 22
	s_nop 1
	v_writelane_b32 v252, s31, 23
	s_branch .LBB0_24
.LBB0_22:
	s_or_b64 exec, exec, s[0:1]
	s_mov_b64 s[0:1], 0
	s_waitcnt lgkmcnt(0)
	s_barrier

.LBB0_1531:
	v_readlane_b32 s2, v251, 42
	v_readlane_b32 s3, v251, 43
	v_cvt_f32_u32_e32 v1, v2
	v_sub_u32_e32 v4, 0, v2
	v_rcp_iflag_f32_e32 v1, v1
	s_nop 1
	global_atomic_add v3, v32, v188, s[2:3] sc0
	v_mul_f32_e32 v1, 0x4f7ffffe, v1
	v_cvt_u32_f32_e32 v1, v1
	v_mul_lo_u32 v4, v4, v1
	v_mul_hi_u32 v4, v1, v4
	v_add_u32_e32 v1, v1, v4
	s_waitcnt vmcnt(0)
	v_mul_hi_u32 v1, v3, v1
	v_mul_lo_u32 v4, v1, v2
	v_sub_u32_e32 v4, v3, v4
	v_add_u32_e32 v5, 1, v1
	v_cmp_ge_u32_e32 vcc, v4, v2
	v_add_u32_e32 v3, 1, v3
	s_nop 0
	v_cndmask_b32_e32 v1, v1, v5, vcc
	v_sub_u32_e32 v5, v4, v2
	v_cndmask_b32_e32 v4, v4, v5, vcc
	v_add_u32_e32 v5, 1, v1
	v_cmp_ge_u32_e32 vcc, v4, v2
	s_nop 1
	v_cndmask_b32_e32 v1, v1, v5, vcc
	v_mul_lo_u32 v4, v2, v1
	v_add_u32_e32 v2, v4, v2
	v_cmp_ne_u32_e32 vcc, v3, v2
	s_waitcnt lgkmcnt(0)
	v_add_u32_e32 v5, 1, v1
	v_mul_lo_u32 v4, v5, v0
	v_readlane_b32 s4, v251, 46
	v_readlane_b32 s5, v251, 47
	s_nop 4
	s_cbranch_vccnz .Lxb_poll
	buffer_wbl2 sc1
	s_waitcnt vmcnt(0)
	global_atomic_add v32, v188, s[4:5]
.Lxb_poll:
	s_mov_b32 s16, 0
.Lxb_spin:
	global_load_dword v6, v32, s[4:5] sc1
	s_waitcnt vmcnt(0)
	v_sub_u32_e32 v6, v6, v4
	v_cmp_gt_i32_e32 vcc, 0, v6
	s_cbranch_vccz .Lxb_done
	s_sleep 1
	s_add_i32 s16, s16, 1
	s_and_b32 s12, s16, 0xff
	s_cmp_lg_u32 s12, 0
	s_cbranch_scc1 .Lxb_spin
	global_load_dword v6, v32, s[64:65] sc1
	s_waitcnt vmcnt(0)
	v_cmp_ne_u32_e32 vcc, 0, v6
	s_cbranch_vccnz .Lxb_done
	s_cmp_lt_u32 s16, 0x40001
	s_cbranch_scc1 .Lxb_spin
	global_atomic_add v32, v188, s[64:65]
.Lxb_done:
	s_waitcnt vmcnt(0)
	buffer_inv sc1
	s_waitcnt vmcnt(0)
	s_getpc_b64 s[98:99]
